# K-loops of the two K=1024/4096 residual GEMMs shifted by 4 bytes
# speedup vs baseline: 1.0052x; 1.0052x over previous
.LBB0_332:
	s_add_u32 s24, s6, 0x100
	s_addc_u32 s38, s7, 0
	s_add_u32 s6, s8, 0x8000
	v_mov_b32_e32 v0, 0
	s_addc_u32 s7, s9, 0
	s_mov_b32 s8, 0
	v_mov_b32_e32 v1, v0
	v_mov_b32_e32 v2, v0
	v_mov_b32_e32 v3, v0
	v_mov_b32_e32 v4, v0
	v_mov_b32_e32 v5, v0
	v_mov_b32_e32 v6, v0
	v_mov_b32_e32 v7, v0
	v_mov_b32_e32 v16, v0
	v_mov_b32_e32 v17, v0
	v_mov_b32_e32 v18, v0
	v_mov_b32_e32 v19, v0
	v_mov_b32_e32 v20, v0
	v_mov_b32_e32 v21, v0
	v_mov_b32_e32 v22, v0
	v_mov_b32_e32 v23, v0
	v_mov_b32_e32 v32, v0
	v_mov_b32_e32 v33, v0
	v_mov_b32_e32 v34, v0
	v_mov_b32_e32 v35, v0
	v_mov_b32_e32 v36, v0
	v_mov_b32_e32 v37, v0
	v_mov_b32_e32 v38, v0
	v_mov_b32_e32 v39, v0
	v_mov_b32_e32 v48, v0
	v_mov_b32_e32 v49, v0
	v_mov_b32_e32 v50, v0
	v_mov_b32_e32 v51, v0
	v_mov_b32_e32 v52, v0
	v_mov_b32_e32 v53, v0
	v_mov_b32_e32 v54, v0
	v_mov_b32_e32 v55, v0
	v_mov_b32_e32 v8, v0
	v_mov_b32_e32 v9, v0
	v_mov_b32_e32 v10, v0
	v_mov_b32_e32 v11, v0
	v_mov_b32_e32 v12, v0
	v_mov_b32_e32 v13, v0
	v_mov_b32_e32 v14, v0
	v_mov_b32_e32 v15, v0
	v_mov_b32_e32 v24, v0
	v_mov_b32_e32 v25, v0
	v_mov_b32_e32 v26, v0
	v_mov_b32_e32 v27, v0
	v_mov_b32_e32 v28, v0
	v_mov_b32_e32 v29, v0
	v_mov_b32_e32 v30, v0
	v_mov_b32_e32 v31, v0
	v_mov_b32_e32 v40, v0
	v_mov_b32_e32 v41, v0
	v_mov_b32_e32 v42, v0
	v_mov_b32_e32 v43, v0
	v_mov_b32_e32 v44, v0
	v_mov_b32_e32 v45, v0
	v_mov_b32_e32 v46, v0
	v_mov_b32_e32 v47, v0
	v_mov_b32_e32 v56, v0
	v_mov_b32_e32 v57, v0
	v_mov_b32_e32 v58, v0
	v_mov_b32_e32 v59, v0
	v_mov_b32_e32 v60, v0
	v_mov_b32_e32 v61, v0
	v_mov_b32_e32 v62, v0
	v_mov_b32_e32 v63, v0
	v_mov_b32_e32 v64, v0
	v_mov_b32_e32 v65, v0
	v_mov_b32_e32 v66, v0
	v_mov_b32_e32 v67, v0
	v_mov_b32_e32 v68, v0
	v_mov_b32_e32 v69, v0
	v_mov_b32_e32 v70, v0
	v_mov_b32_e32 v71, v0
	v_mov_b32_e32 v80, v0
	v_mov_b32_e32 v81, v0
	v_mov_b32_e32 v82, v0
	v_mov_b32_e32 v83, v0
	v_mov_b32_e32 v84, v0
	v_mov_b32_e32 v85, v0
	v_mov_b32_e32 v86, v0
	v_mov_b32_e32 v87, v0
	v_mov_b32_e32 v96, v0
	v_mov_b32_e32 v97, v0
	v_mov_b32_e32 v98, v0
	v_mov_b32_e32 v99, v0
	v_mov_b32_e32 v100, v0
	v_mov_b32_e32 v101, v0
	v_mov_b32_e32 v102, v0
	v_mov_b32_e32 v103, v0
	v_mov_b32_e32 v112, v0
	v_mov_b32_e32 v113, v0
	v_mov_b32_e32 v114, v0
	v_mov_b32_e32 v115, v0
	v_mov_b32_e32 v116, v0
	v_mov_b32_e32 v117, v0
	v_mov_b32_e32 v118, v0
	v_mov_b32_e32 v119, v0
	v_mov_b32_e32 v72, v0
	v_mov_b32_e32 v73, v0
	v_mov_b32_e32 v74, v0
	v_mov_b32_e32 v75, v0
	v_mov_b32_e32 v76, v0
	v_mov_b32_e32 v77, v0
	v_mov_b32_e32 v78, v0
	v_mov_b32_e32 v79, v0
	v_mov_b32_e32 v88, v0
	v_mov_b32_e32 v89, v0
	v_mov_b32_e32 v90, v0
	v_mov_b32_e32 v91, v0
	v_mov_b32_e32 v92, v0
	v_mov_b32_e32 v93, v0
	v_mov_b32_e32 v94, v0
	v_mov_b32_e32 v95, v0
	v_mov_b32_e32 v104, v0
	v_mov_b32_e32 v105, v0
	v_mov_b32_e32 v106, v0
	v_mov_b32_e32 v107, v0
	v_mov_b32_e32 v108, v0
	v_mov_b32_e32 v109, v0
	v_mov_b32_e32 v110, v0
	v_mov_b32_e32 v111, v0
	v_mov_b32_e32 v120, v0
	v_mov_b32_e32 v121, v0
	v_mov_b32_e32 v122, v0
	v_mov_b32_e32 v123, v0
	v_mov_b32_e32 v124, v0
	v_mov_b32_e32 v125, v0
	v_mov_b32_e32 v126, v0
	v_mov_b32_e32 v127, v0
	s_nop 0
.LBB0_333:
	s_add_i32 s56, s8, 2
	s_add_u32 s9, s6, 0x8000
	s_addc_u32 s10, s7, 0
	s_cmp_eq_u32 s94, s8
	s_cselect_b32 s11, s43, s10
	s_cselect_b32 s10, s42, s9
	s_cselect_b32 s60, s54, s24
	s_cselect_b32 s61, s55, s38
	s_add_u32 s8, s10, 0x8000
	s_addc_u32 s9, s11, 0
	s_add_i32 s35, 0, 0x10000
	s_add_i32 s57, 0, 0x14000
	v_add_u32_e32 v142, s35, v178
	v_add_u32_e32 v168, s57, v178
	ds_read_b128 v[128:131], v142
	ds_read_b128 v[132:135], v142 offset:1024
	ds_read_b128 v[136:139], v142 offset:2048
	ds_read_b128 v[142:145], v142 offset:3072
	ds_read_b128 v[146:149], v168
	ds_read_b128 v[150:153], v168 offset:1024
	ds_read_b128 v[154:157], v168 offset:2048
	ds_read_b128 v[168:171], v168 offset:3072
	v_lshl_add_u64 v[176:177], s[6:7], 0, v[164:165]
	s_add_i32 m0, s75, 0xc000
	ds_read_b128 v[172:175], v179
	ds_read_b128 v[180:183], v179 offset:1024
	ds_read_b128 v[184:187], v179 offset:2048
	ds_read_b128 v[188:191], v179 offset:3072
	ds_read_b128 v[192:195], v179 offset:4096
	ds_read_b128 v[200:203], v179 offset:5120
	ds_read_b128 v[206:209], v179 offset:6144
	ds_read_b128 v[210:213], v179 offset:7168
	global_load_lds_dwordx4 v[176:177], off
	v_lshl_add_u64 v[176:177], s[6:7], 0, v[166:167]
	s_add_i32 m0, s75, 0xe000
	s_nop 0
	global_load_lds_dwordx4 v[176:177], off
	s_waitcnt vmcnt(8)
	s_waitcnt lgkmcnt(0)
	s_barrier
	v_mfma_f32_16x16x32_bf16 v[124:127], v[128:131], v[172:175], v[124:127]
	s_setprio 1
	v_mfma_f32_16x16x32_bf16 v[120:123], v[136:139], v[172:175], v[120:123]
	v_mfma_f32_16x16x32_bf16 v[108:111], v[128:131], v[184:187], v[108:111]
	v_mfma_f32_16x16x32_bf16 v[104:107], v[136:139], v[184:187], v[104:107]
	v_mfma_f32_16x16x32_bf16 v[92:95], v[128:131], v[192:195], v[92:95]
	v_mfma_f32_16x16x32_bf16 v[88:91], v[136:139], v[192:195], v[88:91]
	v_mfma_f32_16x16x32_bf16 v[76:79], v[128:131], v[206:209], v[76:79]
	v_mfma_f32_16x16x32_bf16 v[72:75], v[136:139], v[206:209], v[72:75]
	v_mfma_f32_16x16x32_bf16 v[124:127], v[132:135], v[180:183], v[124:127]
	v_mfma_f32_16x16x32_bf16 v[120:123], v[142:145], v[180:183], v[120:123]
	v_mfma_f32_16x16x32_bf16 v[108:111], v[132:135], v[188:191], v[108:111]
	v_mfma_f32_16x16x32_bf16 v[104:107], v[142:145], v[188:191], v[104:107]
	v_mfma_f32_16x16x32_bf16 v[92:95], v[132:135], v[200:203], v[92:95]
	v_mfma_f32_16x16x32_bf16 v[88:91], v[142:145], v[200:203], v[88:91]
	v_mfma_f32_16x16x32_bf16 v[76:79], v[132:135], v[210:213], v[76:79]
	v_mfma_f32_16x16x32_bf16 v[72:75], v[142:145], v[210:213], v[72:75]
	v_mfma_f32_16x16x32_bf16 v[116:119], v[146:149], v[172:175], v[116:119]
	v_mfma_f32_16x16x32_bf16 v[112:115], v[154:157], v[172:175], v[112:115]
	v_mfma_f32_16x16x32_bf16 v[100:103], v[146:149], v[184:187], v[100:103]
	v_mfma_f32_16x16x32_bf16 v[96:99], v[154:157], v[184:187], v[96:99]
	v_mfma_f32_16x16x32_bf16 v[84:87], v[146:149], v[192:195], v[84:87]
	v_mfma_f32_16x16x32_bf16 v[80:83], v[154:157], v[192:195], v[80:83]
	v_mfma_f32_16x16x32_bf16 v[68:71], v[146:149], v[206:209], v[68:71]
	v_mfma_f32_16x16x32_bf16 v[64:67], v[154:157], v[206:209], v[64:67]
	v_mfma_f32_16x16x32_bf16 v[116:119], v[150:153], v[180:183], v[116:119]
	v_mfma_f32_16x16x32_bf16 v[112:115], v[168:171], v[180:183], v[112:115]
	v_mfma_f32_16x16x32_bf16 v[100:103], v[150:153], v[188:191], v[100:103]
	v_mfma_f32_16x16x32_bf16 v[96:99], v[168:171], v[188:191], v[96:99]
	v_mfma_f32_16x16x32_bf16 v[84:87], v[150:153], v[200:203], v[84:87]
	v_mfma_f32_16x16x32_bf16 v[80:83], v[168:171], v[200:203], v[80:83]
	v_mfma_f32_16x16x32_bf16 v[68:71], v[150:153], v[210:213], v[68:71]
	v_mfma_f32_16x16x32_bf16 v[64:67], v[168:171], v[210:213], v[64:67]
	s_barrier
	s_setprio 0
	s_add_i32 s35, s35, s74
	v_lshl_add_u64 v[176:177], s[60:61], 0, v[140:141]
	s_mov_b32 m0, s35
	ds_read_b128 v[172:175], v179 offset:16384
	ds_read_b128 v[180:183], v179 offset:17408
	ds_read_b128 v[184:187], v179 offset:18432
	ds_read_b128 v[188:191], v179 offset:19456
	ds_read_b128 v[192:195], v179 offset:20480
	ds_read_b128 v[200:203], v179 offset:21504
	ds_read_b128 v[206:209], v179 offset:22528
	ds_read_b128 v[210:213], v179 offset:23552
	global_load_lds_dwordx4 v[176:177], off
	s_add_i32 m0, s35, 0x2000
	v_lshl_add_u64 v[196:197], s[60:61], 0, v[158:159]
	s_add_u32 s60, s60, s13
	s_addc_u32 s61, s61, 0
	s_add_i32 s35, s57, s74
	global_load_lds_dwordx4 v[196:197], off
	v_lshl_add_u64 v[198:199], s[60:61], 0, v[140:141]
	s_mov_b32 m0, s35
	v_lshl_add_u64 v[204:205], s[60:61], 0, v[158:159]
	global_load_lds_dwordx4 v[198:199], off
	s_add_i32 m0, s35, 0x2000
	v_lshl_add_u64 v[214:215], s[10:11], 0, v[162:163]
	global_load_lds_dwordx4 v[204:205], off
	s_mov_b32 m0, s75
	s_nop 0
	global_load_lds_dwordx4 v[214:215], off
	v_lshl_add_u64 v[214:215], s[10:11], 0, v[160:161]
	s_mov_b32 m0, s26
	s_nop 0
	global_load_lds_dwordx4 v[214:215], off
	s_waitcnt vmcnt(8)
	s_waitcnt lgkmcnt(0)
	s_barrier
	v_mfma_f32_16x16x32_bf16 v[60:63], v[128:131], v[172:175], v[60:63]
	s_setprio 1
	v_mfma_f32_16x16x32_bf16 v[56:59], v[136:139], v[172:175], v[56:59]
	v_mfma_f32_16x16x32_bf16 v[44:47], v[128:131], v[184:187], v[44:47]
	v_mfma_f32_16x16x32_bf16 v[40:43], v[136:139], v[184:187], v[40:43]
	v_mfma_f32_16x16x32_bf16 v[28:31], v[128:131], v[192:195], v[28:31]
	v_mfma_f32_16x16x32_bf16 v[24:27], v[136:139], v[192:195], v[24:27]
	v_mfma_f32_16x16x32_bf16 v[12:15], v[128:131], v[206:209], v[12:15]
	v_mfma_f32_16x16x32_bf16 v[8:11], v[136:139], v[206:209], v[8:11]
	v_mfma_f32_16x16x32_bf16 v[60:63], v[132:135], v[180:183], v[60:63]
	v_mfma_f32_16x16x32_bf16 v[56:59], v[142:145], v[180:183], v[56:59]
	v_mfma_f32_16x16x32_bf16 v[44:47], v[132:135], v[188:191], v[44:47]
	v_mfma_f32_16x16x32_bf16 v[40:43], v[142:145], v[188:191], v[40:43]
	v_mfma_f32_16x16x32_bf16 v[28:31], v[132:135], v[200:203], v[28:31]
	v_mfma_f32_16x16x32_bf16 v[24:27], v[142:145], v[200:203], v[24:27]
	v_mfma_f32_16x16x32_bf16 v[12:15], v[132:135], v[210:213], v[12:15]
	v_mfma_f32_16x16x32_bf16 v[8:11], v[142:145], v[210:213], v[8:11]
	v_mfma_f32_16x16x32_bf16 v[52:55], v[146:149], v[172:175], v[52:55]
	v_mfma_f32_16x16x32_bf16 v[48:51], v[154:157], v[172:175], v[48:51]
	v_mfma_f32_16x16x32_bf16 v[36:39], v[146:149], v[184:187], v[36:39]
	v_mfma_f32_16x16x32_bf16 v[32:35], v[154:157], v[184:187], v[32:35]
	v_mfma_f32_16x16x32_bf16 v[20:23], v[146:149], v[192:195], v[20:23]
	v_mfma_f32_16x16x32_bf16 v[16:19], v[154:157], v[192:195], v[16:19]
	v_mfma_f32_16x16x32_bf16 v[4:7], v[146:149], v[206:209], v[4:7]
	v_mfma_f32_16x16x32_bf16 v[0:3], v[154:157], v[206:209], v[0:3]
	v_mfma_f32_16x16x32_bf16 v[52:55], v[150:153], v[180:183], v[52:55]
	v_mfma_f32_16x16x32_bf16 v[48:51], v[168:171], v[180:183], v[48:51]
	v_mfma_f32_16x16x32_bf16 v[36:39], v[150:153], v[188:191], v[36:39]
	v_mfma_f32_16x16x32_bf16 v[32:35], v[168:171], v[188:191], v[32:35]
	v_mfma_f32_16x16x32_bf16 v[20:23], v[150:153], v[200:203], v[20:23]
	v_mfma_f32_16x16x32_bf16 v[16:19], v[168:171], v[200:203], v[16:19]
	v_mfma_f32_16x16x32_bf16 v[4:7], v[150:153], v[210:213], v[4:7]
	v_mfma_f32_16x16x32_bf16 v[0:3], v[168:171], v[210:213], v[0:3]
	s_barrier
	s_setprio 0
	s_add_i32 s35, 0, 0x18000
	s_add_i32 s57, 0, 0x1c000
	v_add_u32_e32 v142, s35, v178
	v_add_u32_e32 v168, s57, v178
	ds_read_b128 v[128:131], v142
	ds_read_b128 v[132:135], v142 offset:1024
	ds_read_b128 v[136:139], v142 offset:2048
	ds_read_b128 v[142:145], v142 offset:3072
	ds_read_b128 v[146:149], v168
	ds_read_b128 v[150:153], v168 offset:1024
	ds_read_b128 v[154:157], v168 offset:2048
	ds_read_b128 v[168:171], v168 offset:3072
	s_add_u32 s10, s10, s48
	s_addc_u32 s11, s11, 0
	s_mov_b32 m0, s27
	v_lshl_add_u64 v[214:215], s[10:11], 0, v[162:163]
	ds_read_b128 v[172:175], v179 offset:32768
	ds_read_b128 v[180:183], v179 offset:33792
	ds_read_b128 v[184:187], v179 offset:34816
	ds_read_b128 v[188:191], v179 offset:35840
	ds_read_b128 v[192:195], v179 offset:36864
	ds_read_b128 v[200:203], v179 offset:37888
	ds_read_b128 v[206:209], v179 offset:38912
	ds_read_b128 v[210:213], v179 offset:39936
	global_load_lds_dwordx4 v[214:215], off
	v_lshl_add_u64 v[214:215], s[10:11], 0, v[160:161]
	s_mov_b32 m0, s15
	s_nop 0
	global_load_lds_dwordx4 v[214:215], off
	s_waitcnt vmcnt(8)
	s_waitcnt lgkmcnt(0)
	s_barrier
	v_mfma_f32_16x16x32_bf16 v[124:127], v[128:131], v[172:175], v[124:127]
	s_setprio 1
	v_mfma_f32_16x16x32_bf16 v[120:123], v[136:139], v[172:175], v[120:123]
	v_mfma_f32_16x16x32_bf16 v[108:111], v[128:131], v[184:187], v[108:111]
	v_mfma_f32_16x16x32_bf16 v[104:107], v[136:139], v[184:187], v[104:107]
	v_mfma_f32_16x16x32_bf16 v[92:95], v[128:131], v[192:195], v[92:95]
	v_mfma_f32_16x16x32_bf16 v[88:91], v[136:139], v[192:195], v[88:91]
	v_mfma_f32_16x16x32_bf16 v[76:79], v[128:131], v[206:209], v[76:79]
	v_mfma_f32_16x16x32_bf16 v[72:75], v[136:139], v[206:209], v[72:75]
	v_mfma_f32_16x16x32_bf16 v[124:127], v[132:135], v[180:183], v[124:127]
	v_mfma_f32_16x16x32_bf16 v[120:123], v[142:145], v[180:183], v[120:123]
	v_mfma_f32_16x16x32_bf16 v[108:111], v[132:135], v[188:191], v[108:111]
	v_mfma_f32_16x16x32_bf16 v[104:107], v[142:145], v[188:191], v[104:107]
	v_mfma_f32_16x16x32_bf16 v[92:95], v[132:135], v[200:203], v[92:95]
	v_mfma_f32_16x16x32_bf16 v[88:91], v[142:145], v[200:203], v[88:91]
	v_mfma_f32_16x16x32_bf16 v[76:79], v[132:135], v[210:213], v[76:79]
	v_mfma_f32_16x16x32_bf16 v[72:75], v[142:145], v[210:213], v[72:75]
	v_mfma_f32_16x16x32_bf16 v[116:119], v[146:149], v[172:175], v[116:119]
	v_mfma_f32_16x16x32_bf16 v[112:115], v[154:157], v[172:175], v[112:115]
	v_mfma_f32_16x16x32_bf16 v[100:103], v[146:149], v[184:187], v[100:103]
	v_mfma_f32_16x16x32_bf16 v[96:99], v[154:157], v[184:187], v[96:99]
	v_mfma_f32_16x16x32_bf16 v[84:87], v[146:149], v[192:195], v[84:87]
	v_mfma_f32_16x16x32_bf16 v[80:83], v[154:157], v[192:195], v[80:83]
	v_mfma_f32_16x16x32_bf16 v[68:71], v[146:149], v[206:209], v[68:71]
	v_mfma_f32_16x16x32_bf16 v[64:67], v[154:157], v[206:209], v[64:67]
	v_mfma_f32_16x16x32_bf16 v[116:119], v[150:153], v[180:183], v[116:119]
	v_mfma_f32_16x16x32_bf16 v[112:115], v[168:171], v[180:183], v[112:115]
	v_mfma_f32_16x16x32_bf16 v[100:103], v[150:153], v[188:191], v[100:103]
	v_mfma_f32_16x16x32_bf16 v[96:99], v[168:171], v[188:191], v[96:99]
	v_mfma_f32_16x16x32_bf16 v[84:87], v[150:153], v[200:203], v[84:87]
	v_mfma_f32_16x16x32_bf16 v[80:83], v[168:171], v[200:203], v[80:83]
	v_mfma_f32_16x16x32_bf16 v[68:71], v[150:153], v[210:213], v[68:71]
	v_mfma_f32_16x16x32_bf16 v[64:67], v[168:171], v[210:213], v[64:67]
	s_barrier
	s_setprio 0
	s_add_i32 s10, s35, s74
	v_lshl_add_u64 v[176:177], v[176:177], 0, s[36:37]
	s_mov_b32 m0, s10
	ds_read_b128 v[172:175], v179 offset:49152
	ds_read_b128 v[180:183], v179 offset:50176
	ds_read_b128 v[184:187], v179 offset:51200
	ds_read_b128 v[188:191], v179 offset:52224
	ds_read_b128 v[192:195], v179 offset:53248
	ds_read_b128 v[200:203], v179 offset:54272
	ds_read_b128 v[206:209], v179 offset:55296
	ds_read_b128 v[210:213], v179 offset:56320
	global_load_lds_dwordx4 v[176:177], off
	v_lshl_add_u64 v[176:177], v[196:197], 0, s[36:37]
	s_add_i32 m0, s10, 0x2000
	s_add_i32 s10, s57, s74
	global_load_lds_dwordx4 v[176:177], off
	v_lshl_add_u64 v[176:177], v[198:199], 0, s[36:37]
	s_mov_b32 m0, s10
	s_nop 0
	global_load_lds_dwordx4 v[176:177], off
	v_lshl_add_u64 v[176:177], v[204:205], 0, s[36:37]
	s_add_i32 m0, s10, 0x2000
	s_nop 0
	global_load_lds_dwordx4 v[176:177], off
	v_lshl_add_u64 v[176:177], s[8:9], 0, v[162:163]
	s_mov_b32 m0, s28
	s_nop 0
	global_load_lds_dwordx4 v[176:177], off
	v_lshl_add_u64 v[176:177], s[8:9], 0, v[160:161]
	s_mov_b32 m0, s29
	s_nop 0
	global_load_lds_dwordx4 v[176:177], off
	s_waitcnt vmcnt(8)
	s_waitcnt lgkmcnt(0)
	s_barrier
	v_mfma_f32_16x16x32_bf16 v[60:63], v[128:131], v[172:175], v[60:63]
	s_setprio 1
	v_mfma_f32_16x16x32_bf16 v[56:59], v[136:139], v[172:175], v[56:59]
	v_mfma_f32_16x16x32_bf16 v[44:47], v[128:131], v[184:187], v[44:47]
	v_mfma_f32_16x16x32_bf16 v[40:43], v[136:139], v[184:187], v[40:43]
	v_mfma_f32_16x16x32_bf16 v[28:31], v[128:131], v[192:195], v[28:31]
	v_mfma_f32_16x16x32_bf16 v[24:27], v[136:139], v[192:195], v[24:27]
	v_mfma_f32_16x16x32_bf16 v[12:15], v[128:131], v[206:209], v[12:15]
	v_mfma_f32_16x16x32_bf16 v[8:11], v[136:139], v[206:209], v[8:11]
	v_mfma_f32_16x16x32_bf16 v[60:63], v[132:135], v[180:183], v[60:63]
	v_mfma_f32_16x16x32_bf16 v[56:59], v[142:145], v[180:183], v[56:59]
	v_mfma_f32_16x16x32_bf16 v[44:47], v[132:135], v[188:191], v[44:47]
	v_mfma_f32_16x16x32_bf16 v[40:43], v[142:145], v[188:191], v[40:43]
	v_mfma_f32_16x16x32_bf16 v[28:31], v[132:135], v[200:203], v[28:31]
	v_mfma_f32_16x16x32_bf16 v[24:27], v[142:145], v[200:203], v[24:27]
	v_mfma_f32_16x16x32_bf16 v[12:15], v[132:135], v[210:213], v[12:15]
	v_mfma_f32_16x16x32_bf16 v[8:11], v[142:145], v[210:213], v[8:11]
	v_mfma_f32_16x16x32_bf16 v[52:55], v[146:149], v[172:175], v[52:55]
	v_mfma_f32_16x16x32_bf16 v[48:51], v[154:157], v[172:175], v[48:51]
	v_mfma_f32_16x16x32_bf16 v[36:39], v[146:149], v[184:187], v[36:39]
	v_mfma_f32_16x16x32_bf16 v[32:35], v[154:157], v[184:187], v[32:35]
	v_mfma_f32_16x16x32_bf16 v[20:23], v[146:149], v[192:195], v[20:23]
	v_mfma_f32_16x16x32_bf16 v[16:19], v[154:157], v[192:195], v[16:19]
	v_mfma_f32_16x16x32_bf16 v[4:7], v[146:149], v[206:209], v[4:7]
	v_mfma_f32_16x16x32_bf16 v[0:3], v[154:157], v[206:209], v[0:3]
	v_mfma_f32_16x16x32_bf16 v[52:55], v[150:153], v[180:183], v[52:55]
	v_mfma_f32_16x16x32_bf16 v[48:51], v[168:171], v[180:183], v[48:51]
	v_mfma_f32_16x16x32_bf16 v[36:39], v[150:153], v[188:191], v[36:39]
	v_mfma_f32_16x16x32_bf16 v[32:35], v[168:171], v[188:191], v[32:35]
	v_mfma_f32_16x16x32_bf16 v[20:23], v[150:153], v[200:203], v[20:23]
	v_mfma_f32_16x16x32_bf16 v[16:19], v[168:171], v[200:203], v[16:19]
	v_mfma_f32_16x16x32_bf16 v[4:7], v[150:153], v[210:213], v[4:7]
	v_mfma_f32_16x16x32_bf16 v[0:3], v[168:171], v[210:213], v[0:3]
	s_barrier
	s_setprio 0
	s_add_u32 s24, s24, 0x100
	s_addc_u32 s38, s38, 0
	s_add_u32 s6, s6, 0x10000
	s_addc_u32 s7, s7, 0
	s_cmp_ge_u32 s56, s12
	s_mov_b32 s8, s56
	s_cbranch_scc0 .LBB0_333
	s_nop 0
	s_and_b64 vcc, exec, s[52:53]
	s_cbranch_vccz .LBB0_336
	s_barrier

.LBB0_374:
	s_add_u32 s6, s6, 0x80
	s_addc_u32 s7, s7, 0
	s_add_u32 s10, s8, 0x100
	v_mov_b32_e32 v0, 0
	s_addc_u32 s11, s9, 0
	s_mov_b32 s8, 0
	v_mov_b32_e32 v1, v0
	v_mov_b32_e32 v2, v0
	v_mov_b32_e32 v3, v0
	v_mov_b32_e32 v4, v0
	v_mov_b32_e32 v5, v0
	v_mov_b32_e32 v6, v0
	v_mov_b32_e32 v7, v0
	v_mov_b32_e32 v16, v0
	v_mov_b32_e32 v17, v0
	v_mov_b32_e32 v18, v0
	v_mov_b32_e32 v19, v0
	v_mov_b32_e32 v20, v0
	v_mov_b32_e32 v21, v0
	v_mov_b32_e32 v22, v0
	v_mov_b32_e32 v23, v0
	v_mov_b32_e32 v32, v0
	v_mov_b32_e32 v33, v0
	v_mov_b32_e32 v34, v0
	v_mov_b32_e32 v35, v0
	v_mov_b32_e32 v36, v0
	v_mov_b32_e32 v37, v0
	v_mov_b32_e32 v38, v0
	v_mov_b32_e32 v39, v0
	v_mov_b32_e32 v48, v0
	v_mov_b32_e32 v49, v0
	v_mov_b32_e32 v50, v0
	v_mov_b32_e32 v51, v0
	v_mov_b32_e32 v52, v0
	v_mov_b32_e32 v53, v0
	v_mov_b32_e32 v54, v0
	v_mov_b32_e32 v55, v0
	v_mov_b32_e32 v8, v0
	v_mov_b32_e32 v9, v0
	v_mov_b32_e32 v10, v0
	v_mov_b32_e32 v11, v0
	v_mov_b32_e32 v12, v0
	v_mov_b32_e32 v13, v0
	v_mov_b32_e32 v14, v0
	v_mov_b32_e32 v15, v0
	v_mov_b32_e32 v24, v0
	v_mov_b32_e32 v25, v0
	v_mov_b32_e32 v26, v0
	v_mov_b32_e32 v27, v0
	v_mov_b32_e32 v28, v0
	v_mov_b32_e32 v29, v0
	v_mov_b32_e32 v30, v0
	v_mov_b32_e32 v31, v0
	v_mov_b32_e32 v40, v0
	v_mov_b32_e32 v41, v0
	v_mov_b32_e32 v42, v0
	v_mov_b32_e32 v43, v0
	v_mov_b32_e32 v44, v0
	v_mov_b32_e32 v45, v0
	v_mov_b32_e32 v46, v0
	v_mov_b32_e32 v47, v0
	v_mov_b32_e32 v56, v0
	v_mov_b32_e32 v57, v0
	v_mov_b32_e32 v58, v0
	v_mov_b32_e32 v59, v0
	v_mov_b32_e32 v60, v0
	v_mov_b32_e32 v61, v0
	v_mov_b32_e32 v62, v0
	v_mov_b32_e32 v63, v0
	v_mov_b32_e32 v64, v0
	v_mov_b32_e32 v65, v0
	v_mov_b32_e32 v66, v0
	v_mov_b32_e32 v67, v0
	v_mov_b32_e32 v68, v0
	v_mov_b32_e32 v69, v0
	v_mov_b32_e32 v70, v0
	v_mov_b32_e32 v71, v0
	v_mov_b32_e32 v80, v0
	v_mov_b32_e32 v81, v0
	v_mov_b32_e32 v82, v0
	v_mov_b32_e32 v83, v0
	v_mov_b32_e32 v84, v0
	v_mov_b32_e32 v85, v0
	v_mov_b32_e32 v86, v0
	v_mov_b32_e32 v87, v0
	v_mov_b32_e32 v96, v0
	v_mov_b32_e32 v97, v0
	v_mov_b32_e32 v98, v0
	v_mov_b32_e32 v99, v0
	v_mov_b32_e32 v100, v0
	v_mov_b32_e32 v101, v0
	v_mov_b32_e32 v102, v0
	v_mov_b32_e32 v103, v0
	v_mov_b32_e32 v112, v0
	v_mov_b32_e32 v113, v0
	v_mov_b32_e32 v114, v0
	v_mov_b32_e32 v115, v0
	v_mov_b32_e32 v116, v0
	v_mov_b32_e32 v117, v0
	v_mov_b32_e32 v118, v0
	v_mov_b32_e32 v119, v0
	v_mov_b32_e32 v72, v0
	v_mov_b32_e32 v73, v0
	v_mov_b32_e32 v74, v0
	v_mov_b32_e32 v75, v0
	v_mov_b32_e32 v76, v0
	v_mov_b32_e32 v77, v0
	v_mov_b32_e32 v78, v0
	v_mov_b32_e32 v79, v0
	v_mov_b32_e32 v88, v0
	v_mov_b32_e32 v89, v0
	v_mov_b32_e32 v90, v0
	v_mov_b32_e32 v91, v0
	v_mov_b32_e32 v92, v0
	v_mov_b32_e32 v93, v0
	v_mov_b32_e32 v94, v0
	v_mov_b32_e32 v95, v0
	v_mov_b32_e32 v104, v0
	v_mov_b32_e32 v105, v0
	v_mov_b32_e32 v106, v0
	v_mov_b32_e32 v107, v0
	v_mov_b32_e32 v108, v0
	v_mov_b32_e32 v109, v0
	v_mov_b32_e32 v110, v0
	v_mov_b32_e32 v111, v0
	v_mov_b32_e32 v120, v0
	v_mov_b32_e32 v121, v0
	v_mov_b32_e32 v122, v0
	v_mov_b32_e32 v123, v0
	v_mov_b32_e32 v124, v0
	v_mov_b32_e32 v125, v0
	v_mov_b32_e32 v126, v0
	v_mov_b32_e32 v127, v0
	s_nop 0
.LBB0_375:
	s_add_i32 s24, s8, 2
	s_add_u32 s35, s6, 0x80
	s_addc_u32 s9, s7, 0
	s_add_i32 s38, 0, 0x10000
	s_cmp_eq_u32 s94, s8
	s_cselect_b32 s9, s43, s9
	s_cselect_b32 s8, s42, s35
	s_cselect_b32 s57, s55, s11
	s_cselect_b32 s56, s54, s10
	s_add_i32 s35, 0, 0x14000
	v_add_u32_e32 v142, s38, v178
	v_add_u32_e32 v168, s35, v178
	ds_read_b128 v[128:131], v142
	ds_read_b128 v[132:135], v142 offset:1024
	ds_read_b128 v[136:139], v142 offset:2048
	ds_read_b128 v[142:145], v142 offset:3072
	ds_read_b128 v[146:149], v168
	ds_read_b128 v[150:153], v168 offset:1024
	ds_read_b128 v[154:157], v168 offset:2048
	ds_read_b128 v[168:171], v168 offset:3072
	v_lshl_add_u64 v[176:177], s[6:7], 0, v[164:165]
	s_add_i32 m0, s15, 0xc000
	ds_read_b128 v[172:175], v179
	ds_read_b128 v[180:183], v179 offset:1024
	ds_read_b128 v[184:187], v179 offset:2048
	ds_read_b128 v[188:191], v179 offset:3072
	ds_read_b128 v[192:195], v179 offset:4096
	ds_read_b128 v[200:203], v179 offset:5120
	ds_read_b128 v[206:209], v179 offset:6144
	ds_read_b128 v[210:213], v179 offset:7168
	global_load_lds_dwordx4 v[176:177], off
	v_lshl_add_u64 v[176:177], s[6:7], 0, v[166:167]
	s_add_i32 m0, s15, 0xe000
	s_nop 0
	global_load_lds_dwordx4 v[176:177], off
	s_waitcnt vmcnt(8)
	s_waitcnt lgkmcnt(0)
	s_barrier
	v_mfma_f32_16x16x32_bf16 v[124:127], v[128:131], v[172:175], v[124:127]
	s_setprio 1
	v_mfma_f32_16x16x32_bf16 v[120:123], v[136:139], v[172:175], v[120:123]
	v_mfma_f32_16x16x32_bf16 v[108:111], v[128:131], v[184:187], v[108:111]
	v_mfma_f32_16x16x32_bf16 v[104:107], v[136:139], v[184:187], v[104:107]
	v_mfma_f32_16x16x32_bf16 v[92:95], v[128:131], v[192:195], v[92:95]
	v_mfma_f32_16x16x32_bf16 v[88:91], v[136:139], v[192:195], v[88:91]
	v_mfma_f32_16x16x32_bf16 v[76:79], v[128:131], v[206:209], v[76:79]
	v_mfma_f32_16x16x32_bf16 v[72:75], v[136:139], v[206:209], v[72:75]
	v_mfma_f32_16x16x32_bf16 v[124:127], v[132:135], v[180:183], v[124:127]
	v_mfma_f32_16x16x32_bf16 v[120:123], v[142:145], v[180:183], v[120:123]
	v_mfma_f32_16x16x32_bf16 v[108:111], v[132:135], v[188:191], v[108:111]
	v_mfma_f32_16x16x32_bf16 v[104:107], v[142:145], v[188:191], v[104:107]
	v_mfma_f32_16x16x32_bf16 v[92:95], v[132:135], v[200:203], v[92:95]
	v_mfma_f32_16x16x32_bf16 v[88:91], v[142:145], v[200:203], v[88:91]
	v_mfma_f32_16x16x32_bf16 v[76:79], v[132:135], v[210:213], v[76:79]
	v_mfma_f32_16x16x32_bf16 v[72:75], v[142:145], v[210:213], v[72:75]
	v_mfma_f32_16x16x32_bf16 v[116:119], v[146:149], v[172:175], v[116:119]
	v_mfma_f32_16x16x32_bf16 v[112:115], v[154:157], v[172:175], v[112:115]
	v_mfma_f32_16x16x32_bf16 v[100:103], v[146:149], v[184:187], v[100:103]
	v_mfma_f32_16x16x32_bf16 v[96:99], v[154:157], v[184:187], v[96:99]
	v_mfma_f32_16x16x32_bf16 v[84:87], v[146:149], v[192:195], v[84:87]
	v_mfma_f32_16x16x32_bf16 v[80:83], v[154:157], v[192:195], v[80:83]
	v_mfma_f32_16x16x32_bf16 v[68:71], v[146:149], v[206:209], v[68:71]
	v_mfma_f32_16x16x32_bf16 v[64:67], v[154:157], v[206:209], v[64:67]
	v_mfma_f32_16x16x32_bf16 v[116:119], v[150:153], v[180:183], v[116:119]
	v_mfma_f32_16x16x32_bf16 v[112:115], v[168:171], v[180:183], v[112:115]
	v_mfma_f32_16x16x32_bf16 v[100:103], v[150:153], v[188:191], v[100:103]
	v_mfma_f32_16x16x32_bf16 v[96:99], v[168:171], v[188:191], v[96:99]
	v_mfma_f32_16x16x32_bf16 v[84:87], v[150:153], v[200:203], v[84:87]
	v_mfma_f32_16x16x32_bf16 v[80:83], v[168:171], v[200:203], v[80:83]
	v_mfma_f32_16x16x32_bf16 v[68:71], v[150:153], v[210:213], v[68:71]
	v_mfma_f32_16x16x32_bf16 v[64:67], v[168:171], v[210:213], v[64:67]
	s_barrier
	s_setprio 0
	s_add_i32 s38, s38, s75
	v_lshl_add_u64 v[176:177], s[56:57], 0, v[140:141]
	s_mov_b32 m0, s38
	ds_read_b128 v[172:175], v179 offset:16384
	ds_read_b128 v[180:183], v179 offset:17408
	ds_read_b128 v[184:187], v179 offset:18432
	ds_read_b128 v[188:191], v179 offset:19456
	ds_read_b128 v[192:195], v179 offset:20480
	ds_read_b128 v[200:203], v179 offset:21504
	ds_read_b128 v[206:209], v179 offset:22528
	ds_read_b128 v[210:213], v179 offset:23552
	global_load_lds_dwordx4 v[176:177], off
	s_add_i32 m0, s38, 0x2000
	v_lshl_add_u64 v[196:197], s[56:57], 0, v[158:159]
	s_add_u32 s56, s56, s13
	s_addc_u32 s57, s57, 0
	s_add_i32 s35, s35, s75
	global_load_lds_dwordx4 v[196:197], off
	v_lshl_add_u64 v[198:199], s[56:57], 0, v[140:141]
	s_mov_b32 m0, s35
	v_lshl_add_u64 v[204:205], s[56:57], 0, v[158:159]
	global_load_lds_dwordx4 v[198:199], off
	s_add_i32 m0, s35, 0x2000
	v_lshl_add_u64 v[214:215], s[8:9], 0, v[162:163]
	global_load_lds_dwordx4 v[204:205], off
	s_mov_b32 m0, s15
	v_lshl_add_u64 v[216:217], s[8:9], 0, v[160:161]
	global_load_lds_dwordx4 v[214:215], off
	s_mov_b32 m0, s26
	s_nop 0
	global_load_lds_dwordx4 v[216:217], off
	s_waitcnt vmcnt(8)
	s_waitcnt lgkmcnt(0)
	s_barrier
	v_mfma_f32_16x16x32_bf16 v[60:63], v[128:131], v[172:175], v[60:63]
	s_setprio 1
	v_mfma_f32_16x16x32_bf16 v[56:59], v[136:139], v[172:175], v[56:59]
	v_mfma_f32_16x16x32_bf16 v[44:47], v[128:131], v[184:187], v[44:47]
	v_mfma_f32_16x16x32_bf16 v[40:43], v[136:139], v[184:187], v[40:43]
	v_mfma_f32_16x16x32_bf16 v[28:31], v[128:131], v[192:195], v[28:31]
	v_mfma_f32_16x16x32_bf16 v[24:27], v[136:139], v[192:195], v[24:27]
	v_mfma_f32_16x16x32_bf16 v[12:15], v[128:131], v[206:209], v[12:15]
	v_mfma_f32_16x16x32_bf16 v[8:11], v[136:139], v[206:209], v[8:11]
	v_mfma_f32_16x16x32_bf16 v[60:63], v[132:135], v[180:183], v[60:63]
	v_mfma_f32_16x16x32_bf16 v[56:59], v[142:145], v[180:183], v[56:59]
	v_mfma_f32_16x16x32_bf16 v[44:47], v[132:135], v[188:191], v[44:47]
	v_mfma_f32_16x16x32_bf16 v[40:43], v[142:145], v[188:191], v[40:43]
	v_mfma_f32_16x16x32_bf16 v[28:31], v[132:135], v[200:203], v[28:31]
	v_mfma_f32_16x16x32_bf16 v[24:27], v[142:145], v[200:203], v[24:27]
	v_mfma_f32_16x16x32_bf16 v[12:15], v[132:135], v[210:213], v[12:15]
	v_mfma_f32_16x16x32_bf16 v[8:11], v[142:145], v[210:213], v[8:11]
	v_mfma_f32_16x16x32_bf16 v[52:55], v[146:149], v[172:175], v[52:55]
	v_mfma_f32_16x16x32_bf16 v[48:51], v[154:157], v[172:175], v[48:51]
	v_mfma_f32_16x16x32_bf16 v[36:39], v[146:149], v[184:187], v[36:39]
	v_mfma_f32_16x16x32_bf16 v[32:35], v[154:157], v[184:187], v[32:35]
	v_mfma_f32_16x16x32_bf16 v[20:23], v[146:149], v[192:195], v[20:23]
	v_mfma_f32_16x16x32_bf16 v[16:19], v[154:157], v[192:195], v[16:19]
	v_mfma_f32_16x16x32_bf16 v[4:7], v[146:149], v[206:209], v[4:7]
	v_mfma_f32_16x16x32_bf16 v[0:3], v[154:157], v[206:209], v[0:3]
	v_mfma_f32_16x16x32_bf16 v[52:55], v[150:153], v[180:183], v[52:55]
	v_mfma_f32_16x16x32_bf16 v[48:51], v[168:171], v[180:183], v[48:51]
	v_mfma_f32_16x16x32_bf16 v[36:39], v[150:153], v[188:191], v[36:39]
	v_mfma_f32_16x16x32_bf16 v[32:35], v[168:171], v[188:191], v[32:35]
	v_mfma_f32_16x16x32_bf16 v[20:23], v[150:153], v[200:203], v[20:23]
	v_mfma_f32_16x16x32_bf16 v[16:19], v[168:171], v[200:203], v[16:19]
	v_mfma_f32_16x16x32_bf16 v[4:7], v[150:153], v[210:213], v[4:7]
	v_mfma_f32_16x16x32_bf16 v[0:3], v[168:171], v[210:213], v[0:3]
	s_barrier
	s_setprio 0
	s_add_i32 s35, 0, 0x18000
	s_add_i32 s38, 0, 0x1c000
	v_add_u32_e32 v142, s35, v178
	v_add_u32_e32 v168, s38, v178
	ds_read_b128 v[128:131], v142
	ds_read_b128 v[132:135], v142 offset:1024
	ds_read_b128 v[136:139], v142 offset:2048
	ds_read_b128 v[142:145], v142 offset:3072
	ds_read_b128 v[146:149], v168
	ds_read_b128 v[150:153], v168 offset:1024
	ds_read_b128 v[154:157], v168 offset:2048
	ds_read_b128 v[168:171], v168 offset:3072
	s_add_u32 s8, s8, s48
	s_addc_u32 s9, s9, 0
	s_mov_b32 m0, s27
	v_lshl_add_u64 v[218:219], s[8:9], 0, v[162:163]
	ds_read_b128 v[172:175], v179 offset:32768
	ds_read_b128 v[180:183], v179 offset:33792
	ds_read_b128 v[184:187], v179 offset:34816
	ds_read_b128 v[188:191], v179 offset:35840
	ds_read_b128 v[192:195], v179 offset:36864
	ds_read_b128 v[200:203], v179 offset:37888
	ds_read_b128 v[206:209], v179 offset:38912
	ds_read_b128 v[210:213], v179 offset:39936
	global_load_lds_dwordx4 v[218:219], off
	v_lshl_add_u64 v[218:219], s[8:9], 0, v[160:161]
	s_mov_b32 m0, s28
	s_nop 0
	global_load_lds_dwordx4 v[218:219], off
	s_waitcnt vmcnt(8)
	s_waitcnt lgkmcnt(0)
	s_barrier
	v_mfma_f32_16x16x32_bf16 v[124:127], v[128:131], v[172:175], v[124:127]
	s_setprio 1
	v_mfma_f32_16x16x32_bf16 v[120:123], v[136:139], v[172:175], v[120:123]
	v_mfma_f32_16x16x32_bf16 v[108:111], v[128:131], v[184:187], v[108:111]
	v_mfma_f32_16x16x32_bf16 v[104:107], v[136:139], v[184:187], v[104:107]
	v_mfma_f32_16x16x32_bf16 v[92:95], v[128:131], v[192:195], v[92:95]
	v_mfma_f32_16x16x32_bf16 v[88:91], v[136:139], v[192:195], v[88:91]
	v_mfma_f32_16x16x32_bf16 v[76:79], v[128:131], v[206:209], v[76:79]
	v_mfma_f32_16x16x32_bf16 v[72:75], v[136:139], v[206:209], v[72:75]
	v_mfma_f32_16x16x32_bf16 v[124:127], v[132:135], v[180:183], v[124:127]
	v_mfma_f32_16x16x32_bf16 v[120:123], v[142:145], v[180:183], v[120:123]
	v_mfma_f32_16x16x32_bf16 v[108:111], v[132:135], v[188:191], v[108:111]
	v_mfma_f32_16x16x32_bf16 v[104:107], v[142:145], v[188:191], v[104:107]
	v_mfma_f32_16x16x32_bf16 v[92:95], v[132:135], v[200:203], v[92:95]
	v_mfma_f32_16x16x32_bf16 v[88:91], v[142:145], v[200:203], v[88:91]
	v_mfma_f32_16x16x32_bf16 v[76:79], v[132:135], v[210:213], v[76:79]
	v_mfma_f32_16x16x32_bf16 v[72:75], v[142:145], v[210:213], v[72:75]
	v_mfma_f32_16x16x32_bf16 v[116:119], v[146:149], v[172:175], v[116:119]
	v_mfma_f32_16x16x32_bf16 v[112:115], v[154:157], v[172:175], v[112:115]
	v_mfma_f32_16x16x32_bf16 v[100:103], v[146:149], v[184:187], v[100:103]
	v_mfma_f32_16x16x32_bf16 v[96:99], v[154:157], v[184:187], v[96:99]
	v_mfma_f32_16x16x32_bf16 v[84:87], v[146:149], v[192:195], v[84:87]
	v_mfma_f32_16x16x32_bf16 v[80:83], v[154:157], v[192:195], v[80:83]
	v_mfma_f32_16x16x32_bf16 v[68:71], v[146:149], v[206:209], v[68:71]
	v_mfma_f32_16x16x32_bf16 v[64:67], v[154:157], v[206:209], v[64:67]
	v_mfma_f32_16x16x32_bf16 v[116:119], v[150:153], v[180:183], v[116:119]
	v_mfma_f32_16x16x32_bf16 v[112:115], v[168:171], v[180:183], v[112:115]
	v_mfma_f32_16x16x32_bf16 v[100:103], v[150:153], v[188:191], v[100:103]
	v_mfma_f32_16x16x32_bf16 v[96:99], v[168:171], v[188:191], v[96:99]
	v_mfma_f32_16x16x32_bf16 v[84:87], v[150:153], v[200:203], v[84:87]
	v_mfma_f32_16x16x32_bf16 v[80:83], v[168:171], v[200:203], v[80:83]
	v_mfma_f32_16x16x32_bf16 v[68:71], v[150:153], v[210:213], v[68:71]
	v_mfma_f32_16x16x32_bf16 v[64:67], v[168:171], v[210:213], v[64:67]
	s_barrier
	s_setprio 0
	s_add_i32 s8, s35, s75
	v_lshl_add_u64 v[176:177], v[176:177], 0, s[36:37]
	s_mov_b32 m0, s8
	ds_read_b128 v[172:175], v179 offset:49152
	ds_read_b128 v[180:183], v179 offset:50176
	ds_read_b128 v[184:187], v179 offset:51200
	ds_read_b128 v[188:191], v179 offset:52224
	ds_read_b128 v[192:195], v179 offset:53248
	ds_read_b128 v[200:203], v179 offset:54272
	ds_read_b128 v[206:209], v179 offset:55296
	ds_read_b128 v[210:213], v179 offset:56320
	global_load_lds_dwordx4 v[176:177], off
	v_lshl_add_u64 v[176:177], v[196:197], 0, s[36:37]
	s_add_i32 m0, s8, 0x2000
	s_add_i32 s8, s38, s75
	global_load_lds_dwordx4 v[176:177], off
	v_lshl_add_u64 v[176:177], v[198:199], 0, s[36:37]
	s_mov_b32 m0, s8
	s_nop 0
	global_load_lds_dwordx4 v[176:177], off
	v_lshl_add_u64 v[176:177], v[204:205], 0, s[36:37]
	s_add_i32 m0, s8, 0x2000
	s_nop 0
	global_load_lds_dwordx4 v[176:177], off
	v_lshl_add_u64 v[176:177], v[214:215], 0, s[36:37]
	s_mov_b32 m0, s29
	s_nop 0
	global_load_lds_dwordx4 v[176:177], off
	v_lshl_add_u64 v[176:177], v[216:217], 0, s[36:37]
	s_mov_b32 m0, s58
	s_nop 0
	global_load_lds_dwordx4 v[176:177], off
	s_waitcnt vmcnt(8)
	s_waitcnt lgkmcnt(0)
	s_barrier
	v_mfma_f32_16x16x32_bf16 v[60:63], v[128:131], v[172:175], v[60:63]
	s_setprio 1
	v_mfma_f32_16x16x32_bf16 v[56:59], v[136:139], v[172:175], v[56:59]
	v_mfma_f32_16x16x32_bf16 v[44:47], v[128:131], v[184:187], v[44:47]
	v_mfma_f32_16x16x32_bf16 v[40:43], v[136:139], v[184:187], v[40:43]
	v_mfma_f32_16x16x32_bf16 v[28:31], v[128:131], v[192:195], v[28:31]
	v_mfma_f32_16x16x32_bf16 v[24:27], v[136:139], v[192:195], v[24:27]
	v_mfma_f32_16x16x32_bf16 v[12:15], v[128:131], v[206:209], v[12:15]
	v_mfma_f32_16x16x32_bf16 v[8:11], v[136:139], v[206:209], v[8:11]
	v_mfma_f32_16x16x32_bf16 v[60:63], v[132:135], v[180:183], v[60:63]
	v_mfma_f32_16x16x32_bf16 v[56:59], v[142:145], v[180:183], v[56:59]
	v_mfma_f32_16x16x32_bf16 v[44:47], v[132:135], v[188:191], v[44:47]
	v_mfma_f32_16x16x32_bf16 v[40:43], v[142:145], v[188:191], v[40:43]
	v_mfma_f32_16x16x32_bf16 v[28:31], v[132:135], v[200:203], v[28:31]
	v_mfma_f32_16x16x32_bf16 v[24:27], v[142:145], v[200:203], v[24:27]
	v_mfma_f32_16x16x32_bf16 v[12:15], v[132:135], v[210:213], v[12:15]
	v_mfma_f32_16x16x32_bf16 v[8:11], v[142:145], v[210:213], v[8:11]
	v_mfma_f32_16x16x32_bf16 v[52:55], v[146:149], v[172:175], v[52:55]
	v_mfma_f32_16x16x32_bf16 v[48:51], v[154:157], v[172:175], v[48:51]
	v_mfma_f32_16x16x32_bf16 v[36:39], v[146:149], v[184:187], v[36:39]
	v_mfma_f32_16x16x32_bf16 v[32:35], v[154:157], v[184:187], v[32:35]
	v_mfma_f32_16x16x32_bf16 v[20:23], v[146:149], v[192:195], v[20:23]
	v_mfma_f32_16x16x32_bf16 v[16:19], v[154:157], v[192:195], v[16:19]
	v_mfma_f32_16x16x32_bf16 v[4:7], v[146:149], v[206:209], v[4:7]
	v_mfma_f32_16x16x32_bf16 v[0:3], v[154:157], v[206:209], v[0:3]
	v_mfma_f32_16x16x32_bf16 v[52:55], v[150:153], v[180:183], v[52:55]
	v_mfma_f32_16x16x32_bf16 v[48:51], v[168:171], v[180:183], v[48:51]
	v_mfma_f32_16x16x32_bf16 v[36:39], v[150:153], v[188:191], v[36:39]
	v_mfma_f32_16x16x32_bf16 v[32:35], v[168:171], v[188:191], v[32:35]
	v_mfma_f32_16x16x32_bf16 v[20:23], v[150:153], v[200:203], v[20:23]
	v_mfma_f32_16x16x32_bf16 v[16:19], v[168:171], v[200:203], v[16:19]
	v_mfma_f32_16x16x32_bf16 v[4:7], v[150:153], v[210:213], v[4:7]
	v_mfma_f32_16x16x32_bf16 v[0:3], v[168:171], v[210:213], v[0:3]
	s_barrier
	s_setprio 0
	s_add_u32 s6, s6, 0x100
	s_addc_u32 s7, s7, 0
	s_add_u32 s10, s10, 0x100
	s_addc_u32 s11, s11, 0
	s_cmp_ge_u32 s24, s12
	s_mov_b32 s8, s24
	s_cbranch_scc0 .LBB0_375
	s_nop 0
	s_and_b64 vcc, exec, s[52:53]
	s_cbranch_vccz .LBB0_378
	s_barrier
